# K loop heads aligned to 64 bytes (.p2align 6) on top of the slimmed loops
# speedup vs baseline: 1.0023x; 1.0023x over previous
.LBB0_117:
	s_ashr_i32 s45, s44, 31
	v_cmp_lt_i64_e32 vcc, s[10:11], v[186:187]
	s_lshl_b64 s[10:11], s[44:45], 20
	v_readlane_b32 s46, v254, 52
	v_readlane_b32 s47, v254, 53
	s_add_u32 s46, s46, s10
	s_addc_u32 s47, s47, s11
	s_and_b64 s[10:11], vcc, exec
	v_readlane_b32 s52, v254, 2
	s_cselect_b32 s5, s47, s7
	s_cselect_b32 s33, s46, s6
	s_ashr_i32 s43, s42, 31
	v_readlane_b32 s53, v254, 3
	s_lshl_b64 s[10:11], s[42:43], 20
	s_mov_b64 s[48:49], s[52:53]
	s_add_u32 s48, s48, s10
	s_addc_u32 s49, s49, s11
	s_and_b64 s[10:11], vcc, exec
	s_cselect_b32 s43, s49, s9
	s_cselect_b32 s45, s48, s8
	s_add_u32 s6, s6, 0x80080
	s_addc_u32 s7, s7, 0
	s_add_u32 s51, s8, 0x100
	s_waitcnt lgkmcnt(0)
	v_mov_b32_e32 v0, 0
	s_addc_u32 s52, s9, 0
	s_mov_b32 s53, -2
	v_mov_b32_e32 v1, v0
	v_mov_b32_e32 v2, v0
	v_mov_b32_e32 v3, v0
	v_mov_b32_e32 v8, v0
	v_mov_b32_e32 v9, v0
	v_mov_b32_e32 v10, v0
	v_mov_b32_e32 v11, v0
	v_mov_b32_e32 v16, v0
	v_mov_b32_e32 v17, v0
	v_mov_b32_e32 v18, v0
	v_mov_b32_e32 v19, v0
	v_mov_b32_e32 v24, v0
	v_mov_b32_e32 v25, v0
	v_mov_b32_e32 v26, v0
	v_mov_b32_e32 v27, v0
	v_mov_b32_e32 v32, v0
	v_mov_b32_e32 v33, v0
	v_mov_b32_e32 v34, v0
	v_mov_b32_e32 v35, v0
	v_mov_b32_e32 v40, v0
	v_mov_b32_e32 v41, v0
	v_mov_b32_e32 v42, v0
	v_mov_b32_e32 v43, v0
	v_mov_b32_e32 v48, v0
	v_mov_b32_e32 v49, v0
	v_mov_b32_e32 v50, v0
	v_mov_b32_e32 v51, v0
	v_mov_b32_e32 v56, v0
	v_mov_b32_e32 v57, v0
	v_mov_b32_e32 v58, v0
	v_mov_b32_e32 v59, v0
	v_mov_b32_e32 v4, v0
	v_mov_b32_e32 v5, v0
	v_mov_b32_e32 v6, v0
	v_mov_b32_e32 v7, v0
	v_mov_b32_e32 v12, v0
	v_mov_b32_e32 v13, v0
	v_mov_b32_e32 v14, v0
	v_mov_b32_e32 v15, v0
	v_mov_b32_e32 v20, v0
	v_mov_b32_e32 v21, v0
	v_mov_b32_e32 v22, v0
	v_mov_b32_e32 v23, v0
	v_mov_b32_e32 v28, v0
	v_mov_b32_e32 v29, v0
	v_mov_b32_e32 v30, v0
	v_mov_b32_e32 v31, v0
	v_mov_b32_e32 v36, v0
	v_mov_b32_e32 v37, v0
	v_mov_b32_e32 v38, v0
	v_mov_b32_e32 v39, v0
	v_mov_b32_e32 v44, v0
	v_mov_b32_e32 v45, v0
	v_mov_b32_e32 v46, v0
	v_mov_b32_e32 v47, v0
	v_mov_b32_e32 v52, v0
	v_mov_b32_e32 v53, v0
	v_mov_b32_e32 v54, v0
	v_mov_b32_e32 v55, v0
	v_mov_b32_e32 v60, v0
	v_mov_b32_e32 v61, v0
	v_mov_b32_e32 v62, v0
	v_mov_b32_e32 v63, v0
	v_mov_b32_e32 v64, v0
	v_mov_b32_e32 v65, v0
	v_mov_b32_e32 v66, v0
	v_mov_b32_e32 v67, v0
	v_mov_b32_e32 v72, v0
	v_mov_b32_e32 v73, v0
	v_mov_b32_e32 v74, v0
	v_mov_b32_e32 v75, v0
	v_mov_b32_e32 v80, v0
	v_mov_b32_e32 v81, v0
	v_mov_b32_e32 v82, v0
	v_mov_b32_e32 v83, v0
	v_mov_b32_e32 v88, v0
	v_mov_b32_e32 v89, v0
	v_mov_b32_e32 v90, v0
	v_mov_b32_e32 v91, v0
	v_mov_b32_e32 v96, v0
	v_mov_b32_e32 v97, v0
	v_mov_b32_e32 v98, v0
	v_mov_b32_e32 v99, v0
	v_mov_b32_e32 v104, v0
	v_mov_b32_e32 v105, v0
	v_mov_b32_e32 v106, v0
	v_mov_b32_e32 v107, v0
	v_mov_b32_e32 v112, v0
	v_mov_b32_e32 v113, v0
	v_mov_b32_e32 v114, v0
	v_mov_b32_e32 v115, v0
	v_mov_b32_e32 v120, v0
	v_mov_b32_e32 v121, v0
	v_mov_b32_e32 v122, v0
	v_mov_b32_e32 v123, v0
	v_mov_b32_e32 v68, v0
	v_mov_b32_e32 v69, v0
	v_mov_b32_e32 v70, v0
	v_mov_b32_e32 v71, v0
	v_mov_b32_e32 v76, v0
	v_mov_b32_e32 v77, v0
	v_mov_b32_e32 v78, v0
	v_mov_b32_e32 v79, v0
	v_mov_b32_e32 v84, v0
	v_mov_b32_e32 v85, v0
	v_mov_b32_e32 v86, v0
	v_mov_b32_e32 v87, v0
	v_mov_b32_e32 v92, v0
	v_mov_b32_e32 v93, v0
	v_mov_b32_e32 v94, v0
	v_mov_b32_e32 v95, v0
	v_mov_b32_e32 v100, v0
	v_mov_b32_e32 v101, v0
	v_mov_b32_e32 v102, v0
	v_mov_b32_e32 v103, v0
	v_mov_b32_e32 v108, v0
	v_mov_b32_e32 v109, v0
	v_mov_b32_e32 v110, v0
	v_mov_b32_e32 v111, v0
	v_mov_b32_e32 v116, v0
	v_mov_b32_e32 v117, v0
	v_mov_b32_e32 v118, v0
	v_mov_b32_e32 v119, v0
	v_mov_b32_e32 v124, v0
	v_mov_b32_e32 v125, v0
	v_mov_b32_e32 v126, v0
	v_mov_b32_e32 v127, v0
	v_readlane_b32 s54, v254, 4
	v_readlane_b32 s55, v254, 5
	.p2align	6

.LBB0_1023:
	s_ashr_i32 s21, s20, 31
	s_lshl_b64 s[26:27], s[20:21], 20
	v_readlane_b32 s2, v254, 52
	v_readlane_b32 s3, v254, 53
	s_add_u32 s21, s2, s26
	s_addc_u32 s23, s3, s27
	s_ashr_i32 s25, s24, 31
	s_lshl_b64 s[28:29], s[24:25], 7
	s_add_u32 s26, s21, s28
	s_addc_u32 s27, s23, s29
	s_and_b64 s[58:59], s[38:39], exec
	s_cselect_b32 s21, s27, s5
	s_cselect_b32 s25, s26, s4
	s_ashr_i32 s23, s22, 31
	s_lshl_b64 s[58:59], s[22:23], 20
	s_add_u32 s23, s40, s58
	s_addc_u32 s58, s41, s59
	s_add_u32 s28, s23, s28
	s_addc_u32 s29, s58, s29
	s_and_b64 s[38:39], s[38:39], exec
	s_cselect_b32 s23, s29, s37
	s_cselect_b32 s58, s28, s36
	s_add_i32 s59, s17, -2
	s_add_u32 s4, s4, 0x80080
	s_addc_u32 s5, s5, 0
	s_add_u32 s60, s36, 0x100
	v_mov_b32_e32 v0, 0
	s_addc_u32 s61, s37, 0
	s_mov_b32 s36, 0
	v_mov_b32_e32 v1, v0
	v_mov_b32_e32 v2, v0
	v_mov_b32_e32 v3, v0
	v_mov_b32_e32 v4, v0
	v_mov_b32_e32 v5, v0
	v_mov_b32_e32 v6, v0
	v_mov_b32_e32 v7, v0
	v_mov_b32_e32 v12, v0
	v_mov_b32_e32 v13, v0
	v_mov_b32_e32 v14, v0
	v_mov_b32_e32 v15, v0
	v_mov_b32_e32 v16, v0
	v_mov_b32_e32 v17, v0
	v_mov_b32_e32 v18, v0
	v_mov_b32_e32 v19, v0
	v_mov_b32_e32 v28, v0
	v_mov_b32_e32 v29, v0
	v_mov_b32_e32 v30, v0
	v_mov_b32_e32 v31, v0
	v_mov_b32_e32 v32, v0
	v_mov_b32_e32 v33, v0
	v_mov_b32_e32 v34, v0
	v_mov_b32_e32 v35, v0
	v_mov_b32_e32 v44, v0
	v_mov_b32_e32 v45, v0
	v_mov_b32_e32 v46, v0
	v_mov_b32_e32 v47, v0
	v_mov_b32_e32 v48, v0
	v_mov_b32_e32 v49, v0
	v_mov_b32_e32 v50, v0
	v_mov_b32_e32 v51, v0
	v_mov_b32_e32 v8, v0
	v_mov_b32_e32 v9, v0
	v_mov_b32_e32 v10, v0
	v_mov_b32_e32 v11, v0
	v_mov_b32_e32 v20, v0
	v_mov_b32_e32 v21, v0
	v_mov_b32_e32 v22, v0
	v_mov_b32_e32 v23, v0
	v_mov_b32_e32 v24, v0
	v_mov_b32_e32 v25, v0
	v_mov_b32_e32 v26, v0
	v_mov_b32_e32 v27, v0
	v_mov_b32_e32 v36, v0
	v_mov_b32_e32 v37, v0
	v_mov_b32_e32 v38, v0
	v_mov_b32_e32 v39, v0
	v_mov_b32_e32 v40, v0
	v_mov_b32_e32 v41, v0
	v_mov_b32_e32 v42, v0
	v_mov_b32_e32 v43, v0
	v_mov_b32_e32 v52, v0
	v_mov_b32_e32 v53, v0
	v_mov_b32_e32 v54, v0
	v_mov_b32_e32 v55, v0
	v_mov_b32_e32 v56, v0
	v_mov_b32_e32 v57, v0
	v_mov_b32_e32 v58, v0
	v_mov_b32_e32 v59, v0
	v_mov_b32_e32 v60, v0
	v_mov_b32_e32 v61, v0
	v_mov_b32_e32 v62, v0
	v_mov_b32_e32 v63, v0
	v_mov_b32_e32 v64, v0
	v_mov_b32_e32 v65, v0
	v_mov_b32_e32 v66, v0
	v_mov_b32_e32 v67, v0
	v_mov_b32_e32 v68, v0
	v_mov_b32_e32 v69, v0
	v_mov_b32_e32 v70, v0
	v_mov_b32_e32 v71, v0
	v_mov_b32_e32 v76, v0
	v_mov_b32_e32 v77, v0
	v_mov_b32_e32 v78, v0
	v_mov_b32_e32 v79, v0
	v_mov_b32_e32 v84, v0
	v_mov_b32_e32 v85, v0
	v_mov_b32_e32 v86, v0
	v_mov_b32_e32 v87, v0
	v_mov_b32_e32 v92, v0
	v_mov_b32_e32 v93, v0
	v_mov_b32_e32 v94, v0
	v_mov_b32_e32 v95, v0
	v_mov_b32_e32 v100, v0
	v_mov_b32_e32 v101, v0
	v_mov_b32_e32 v102, v0
	v_mov_b32_e32 v103, v0
	v_mov_b32_e32 v108, v0
	v_mov_b32_e32 v109, v0
	v_mov_b32_e32 v110, v0
	v_mov_b32_e32 v111, v0
	v_mov_b32_e32 v112, v0
	v_mov_b32_e32 v113, v0
	v_mov_b32_e32 v114, v0
	v_mov_b32_e32 v115, v0
	v_mov_b32_e32 v72, v0
	v_mov_b32_e32 v73, v0
	v_mov_b32_e32 v74, v0
	v_mov_b32_e32 v75, v0
	v_mov_b32_e32 v80, v0
	v_mov_b32_e32 v81, v0
	v_mov_b32_e32 v82, v0
	v_mov_b32_e32 v83, v0
	v_mov_b32_e32 v88, v0
	v_mov_b32_e32 v89, v0
	v_mov_b32_e32 v90, v0
	v_mov_b32_e32 v91, v0
	v_mov_b32_e32 v96, v0
	v_mov_b32_e32 v97, v0
	v_mov_b32_e32 v98, v0
	v_mov_b32_e32 v99, v0
	v_mov_b32_e32 v104, v0
	v_mov_b32_e32 v105, v0
	v_mov_b32_e32 v106, v0
	v_mov_b32_e32 v107, v0
	v_mov_b32_e32 v116, v0
	v_mov_b32_e32 v117, v0
	v_mov_b32_e32 v118, v0
	v_mov_b32_e32 v119, v0
	v_mov_b32_e32 v120, v0
	v_mov_b32_e32 v121, v0
	v_mov_b32_e32 v122, v0
	v_mov_b32_e32 v123, v0
	v_mov_b32_e32 v124, v0
	v_mov_b32_e32 v125, v0
	v_mov_b32_e32 v126, v0
	v_mov_b32_e32 v127, v0
	.p2align	6

.LBB0_1166:
	s_ashr_i32 s15, s14, 31
	v_cmp_lt_i64_e32 vcc, s[16:17], v[132:133]
	s_lshl_b64 s[16:17], s[14:15], 20
	v_readlane_b32 s18, v254, 54
	v_readlane_b32 s19, v254, 55
	s_add_u32 s16, s18, s16
	s_addc_u32 s17, s19, s17
	s_and_b64 s[18:19], vcc, exec
	s_cselect_b32 s15, s17, s23
	s_cselect_b32 s49, s16, s22
	s_ashr_i32 s13, s12, 31
	s_lshl_b64 s[18:19], s[12:13], 20
	s_add_u32 s18, s29, s18
	s_addc_u32 s19, s30, s19
	s_and_b64 s[26:27], vcc, exec
	s_cselect_b32 s13, s19, s25
	s_cselect_b32 s50, s18, s24
	s_add_u32 s22, s22, 0x80080
	s_addc_u32 s23, s23, 0
	s_add_u32 s51, s24, 0x100
	v_mov_b32_e32 v0, 0
	s_addc_u32 s52, s25, 0
	s_mov_b32 s53, -2
	v_mov_b32_e32 v1, v0
	v_mov_b32_e32 v2, v0
	v_mov_b32_e32 v3, v0
	v_mov_b32_e32 v4, v0
	v_mov_b32_e32 v5, v0
	v_mov_b32_e32 v6, v0
	v_mov_b32_e32 v7, v0
	v_mov_b32_e32 v12, v0
	v_mov_b32_e32 v13, v0
	v_mov_b32_e32 v14, v0
	v_mov_b32_e32 v15, v0
	v_mov_b32_e32 v20, v0
	v_mov_b32_e32 v21, v0
	v_mov_b32_e32 v22, v0
	v_mov_b32_e32 v23, v0
	v_mov_b32_e32 v28, v0
	v_mov_b32_e32 v29, v0
	v_mov_b32_e32 v30, v0
	v_mov_b32_e32 v31, v0
	v_mov_b32_e32 v36, v0
	v_mov_b32_e32 v37, v0
	v_mov_b32_e32 v38, v0
	v_mov_b32_e32 v39, v0
	v_mov_b32_e32 v44, v0
	v_mov_b32_e32 v45, v0
	v_mov_b32_e32 v46, v0
	v_mov_b32_e32 v47, v0
	v_mov_b32_e32 v52, v0
	v_mov_b32_e32 v53, v0
	v_mov_b32_e32 v54, v0
	v_mov_b32_e32 v55, v0
	v_mov_b32_e32 v8, v0
	v_mov_b32_e32 v9, v0
	v_mov_b32_e32 v10, v0
	v_mov_b32_e32 v11, v0
	v_mov_b32_e32 v16, v0
	v_mov_b32_e32 v17, v0
	v_mov_b32_e32 v18, v0
	v_mov_b32_e32 v19, v0
	v_mov_b32_e32 v24, v0
	v_mov_b32_e32 v25, v0
	v_mov_b32_e32 v26, v0
	v_mov_b32_e32 v27, v0
	v_mov_b32_e32 v32, v0
	v_mov_b32_e32 v33, v0
	v_mov_b32_e32 v34, v0
	v_mov_b32_e32 v35, v0
	v_mov_b32_e32 v40, v0
	v_mov_b32_e32 v41, v0
	v_mov_b32_e32 v42, v0
	v_mov_b32_e32 v43, v0
	v_mov_b32_e32 v48, v0
	v_mov_b32_e32 v49, v0
	v_mov_b32_e32 v50, v0
	v_mov_b32_e32 v51, v0
	v_mov_b32_e32 v56, v0
	v_mov_b32_e32 v57, v0
	v_mov_b32_e32 v58, v0
	v_mov_b32_e32 v59, v0
	v_mov_b32_e32 v60, v0
	v_mov_b32_e32 v61, v0
	v_mov_b32_e32 v62, v0
	v_mov_b32_e32 v63, v0
	v_mov_b32_e32 v64, v0
	v_mov_b32_e32 v65, v0
	v_mov_b32_e32 v66, v0
	v_mov_b32_e32 v67, v0
	v_mov_b32_e32 v68, v0
	v_mov_b32_e32 v69, v0
	v_mov_b32_e32 v70, v0
	v_mov_b32_e32 v71, v0
	v_mov_b32_e32 v76, v0
	v_mov_b32_e32 v77, v0
	v_mov_b32_e32 v78, v0
	v_mov_b32_e32 v79, v0
	v_mov_b32_e32 v84, v0
	v_mov_b32_e32 v85, v0
	v_mov_b32_e32 v86, v0
	v_mov_b32_e32 v87, v0
	v_mov_b32_e32 v92, v0
	v_mov_b32_e32 v93, v0
	v_mov_b32_e32 v94, v0
	v_mov_b32_e32 v95, v0
	v_mov_b32_e32 v100, v0
	v_mov_b32_e32 v101, v0
	v_mov_b32_e32 v102, v0
	v_mov_b32_e32 v103, v0
	v_mov_b32_e32 v108, v0
	v_mov_b32_e32 v109, v0
	v_mov_b32_e32 v110, v0
	v_mov_b32_e32 v111, v0
	v_mov_b32_e32 v112, v0
	v_mov_b32_e32 v113, v0
	v_mov_b32_e32 v114, v0
	v_mov_b32_e32 v115, v0
	v_mov_b32_e32 v72, v0
	v_mov_b32_e32 v73, v0
	v_mov_b32_e32 v74, v0
	v_mov_b32_e32 v75, v0
	v_mov_b32_e32 v80, v0
	v_mov_b32_e32 v81, v0
	v_mov_b32_e32 v82, v0
	v_mov_b32_e32 v83, v0
	v_mov_b32_e32 v88, v0
	v_mov_b32_e32 v89, v0
	v_mov_b32_e32 v90, v0
	v_mov_b32_e32 v91, v0
	v_mov_b32_e32 v96, v0
	v_mov_b32_e32 v97, v0
	v_mov_b32_e32 v98, v0
	v_mov_b32_e32 v99, v0
	v_mov_b32_e32 v104, v0
	v_mov_b32_e32 v105, v0
	v_mov_b32_e32 v106, v0
	v_mov_b32_e32 v107, v0
	v_mov_b32_e32 v116, v0
	v_mov_b32_e32 v117, v0
	v_mov_b32_e32 v118, v0
	v_mov_b32_e32 v119, v0
	v_mov_b32_e32 v120, v0
	v_mov_b32_e32 v121, v0
	v_mov_b32_e32 v122, v0
	v_mov_b32_e32 v123, v0
	v_mov_b32_e32 v124, v0
	v_mov_b32_e32 v125, v0
	v_mov_b32_e32 v126, v0
	v_mov_b32_e32 v127, v0
	.p2align	6

.LBB0_1257:
	s_add_i32 s13, s51, -2
	s_add_u32 s16, s16, 0x160080
	s_addc_u32 s17, s17, 0
	s_add_u32 s52, s18, 0x100
	v_mov_b32_e32 v0, 0
	s_addc_u32 s53, s19, 0
	s_mov_b32 s18, 0
	v_mov_b32_e32 v1, v0
	v_mov_b32_e32 v2, v0
	v_mov_b32_e32 v3, v0
	v_mov_b32_e32 v4, v0
	v_mov_b32_e32 v5, v0
	v_mov_b32_e32 v6, v0
	v_mov_b32_e32 v7, v0
	v_mov_b32_e32 v12, v0
	v_mov_b32_e32 v13, v0
	v_mov_b32_e32 v14, v0
	v_mov_b32_e32 v15, v0
	v_mov_b32_e32 v16, v0
	v_mov_b32_e32 v17, v0
	v_mov_b32_e32 v18, v0
	v_mov_b32_e32 v19, v0
	v_mov_b32_e32 v28, v0
	v_mov_b32_e32 v29, v0
	v_mov_b32_e32 v30, v0
	v_mov_b32_e32 v31, v0
	v_mov_b32_e32 v32, v0
	v_mov_b32_e32 v33, v0
	v_mov_b32_e32 v34, v0
	v_mov_b32_e32 v35, v0
	v_mov_b32_e32 v44, v0
	v_mov_b32_e32 v45, v0
	v_mov_b32_e32 v46, v0
	v_mov_b32_e32 v47, v0
	v_mov_b32_e32 v48, v0
	v_mov_b32_e32 v49, v0
	v_mov_b32_e32 v50, v0
	v_mov_b32_e32 v51, v0
	v_mov_b32_e32 v8, v0
	v_mov_b32_e32 v9, v0
	v_mov_b32_e32 v10, v0
	v_mov_b32_e32 v11, v0
	v_mov_b32_e32 v20, v0
	v_mov_b32_e32 v21, v0
	v_mov_b32_e32 v22, v0
	v_mov_b32_e32 v23, v0
	v_mov_b32_e32 v24, v0
	v_mov_b32_e32 v25, v0
	v_mov_b32_e32 v26, v0
	v_mov_b32_e32 v27, v0
	v_mov_b32_e32 v36, v0
	v_mov_b32_e32 v37, v0
	v_mov_b32_e32 v38, v0
	v_mov_b32_e32 v39, v0
	v_mov_b32_e32 v40, v0
	v_mov_b32_e32 v41, v0
	v_mov_b32_e32 v42, v0
	v_mov_b32_e32 v43, v0
	v_mov_b32_e32 v52, v0
	v_mov_b32_e32 v53, v0
	v_mov_b32_e32 v54, v0
	v_mov_b32_e32 v55, v0
	v_mov_b32_e32 v56, v0
	v_mov_b32_e32 v57, v0
	v_mov_b32_e32 v58, v0
	v_mov_b32_e32 v59, v0
	v_mov_b32_e32 v60, v0
	v_mov_b32_e32 v61, v0
	v_mov_b32_e32 v62, v0
	v_mov_b32_e32 v63, v0
	v_mov_b32_e32 v64, v0
	v_mov_b32_e32 v65, v0
	v_mov_b32_e32 v66, v0
	v_mov_b32_e32 v67, v0
	v_mov_b32_e32 v68, v0
	v_mov_b32_e32 v69, v0
	v_mov_b32_e32 v70, v0
	v_mov_b32_e32 v71, v0
	v_mov_b32_e32 v76, v0
	v_mov_b32_e32 v77, v0
	v_mov_b32_e32 v78, v0
	v_mov_b32_e32 v79, v0
	v_mov_b32_e32 v84, v0
	v_mov_b32_e32 v85, v0
	v_mov_b32_e32 v86, v0
	v_mov_b32_e32 v87, v0
	v_mov_b32_e32 v92, v0
	v_mov_b32_e32 v93, v0
	v_mov_b32_e32 v94, v0
	v_mov_b32_e32 v95, v0
	v_mov_b32_e32 v100, v0
	v_mov_b32_e32 v101, v0
	v_mov_b32_e32 v102, v0
	v_mov_b32_e32 v103, v0
	v_mov_b32_e32 v108, v0
	v_mov_b32_e32 v109, v0
	v_mov_b32_e32 v110, v0
	v_mov_b32_e32 v111, v0
	v_mov_b32_e32 v112, v0
	v_mov_b32_e32 v113, v0
	v_mov_b32_e32 v114, v0
	v_mov_b32_e32 v115, v0
	v_mov_b32_e32 v72, v0
	v_mov_b32_e32 v73, v0
	v_mov_b32_e32 v74, v0
	v_mov_b32_e32 v75, v0
	v_mov_b32_e32 v80, v0
	v_mov_b32_e32 v81, v0
	v_mov_b32_e32 v82, v0
	v_mov_b32_e32 v83, v0
	v_mov_b32_e32 v88, v0
	v_mov_b32_e32 v89, v0
	v_mov_b32_e32 v90, v0
	v_mov_b32_e32 v91, v0
	v_mov_b32_e32 v96, v0
	v_mov_b32_e32 v97, v0
	v_mov_b32_e32 v98, v0
	v_mov_b32_e32 v99, v0
	v_mov_b32_e32 v104, v0
	v_mov_b32_e32 v105, v0
	v_mov_b32_e32 v106, v0
	v_mov_b32_e32 v107, v0
	v_mov_b32_e32 v116, v0
	v_mov_b32_e32 v117, v0
	v_mov_b32_e32 v118, v0
	v_mov_b32_e32 v119, v0
	v_mov_b32_e32 v120, v0
	v_mov_b32_e32 v121, v0
	v_mov_b32_e32 v122, v0
	v_mov_b32_e32 v123, v0
	v_mov_b32_e32 v124, v0
	v_mov_b32_e32 v125, v0
	v_mov_b32_e32 v126, v0
	v_mov_b32_e32 v127, v0
	.p2align	6
